# GEMM: peel first K-step with srcC=0 MFMAs, drop 128 v_mov accumulator zeroing per unit
# speedup vs baseline: 1.0016x; 1.0004x over previous
; #define PG8_STAGE(bufoff, gbase, voff) do { _Pragma("unroll") for (int _i = 0; _i < 2; ++_i) \
;         __builtin_amdgcn_global_load_lds((const unsigned*)((const char*)(gbase) + (voff)[_i]), (LAS unsigned*)(lds + (bufoff) + ldsw + _i * 8192), 16, 0, 0); } while (0)
; #define PG8_LDA(dst, b, h) do { _Pragma("unroll") for (int m = 0; m < 4; ++m) _Pragma("unroll") for (int k = 0; k < 2; ++k) dst[m][k] = *(const LAS bf16x8*)(lds + PG8_SA(b, h) + aoff + m * 2048 + k * 1024); } while (0)
; #define PG8_LDB(dst, b, h) do { _Pragma("unroll") for (int n = 0; n < 2; ++n) _Pragma("unroll") for (int k = 0; k < 2; ++k) dst[n][k] = *(const LAS bf16x8*)(lds + PG8_SB(b, h) + boff + n * 2048 + k * 1024); } while (0)
; #define PG8_MMA(ai, bj, At, Bt) do { __builtin_amdgcn_s_setprio(1); _Pragma("unroll") for (int m = 0; m < 4; ++m) _Pragma("unroll") for (int n = 0; n < 2; ++n) _Pragma("unroll") for (int k = 0; k < 2; ++k) \
;         acc[ai][bj][m][n] = __builtin_amdgcn_mfma_f32_16x16x32_bf16(Bt[n][k], At[m][k], acc[ai][bj][m][n], 0, 0, 0); __builtin_amdgcn_s_setprio(0); } while (0)
; #define PG8_WAIT_L(n) asm volatile("s_waitcnt lgkmcnt(" #n ")" ::: "memory")
; #define PG8_BAR __builtin_amdgcn_s_barrier()
; #define PG8_SCHED __builtin_amdgcn_sched_barrier(0)
; __device__ __forceinline__ void gemm_phase(const int bid, const int nblk, LAS unsigned char* lds, const int garg, const int chunk, const Params& p) {
;     ...
;             PG8_LDB(B0, 0, 0); PG8_SCHED; PG8_LDA(At, 0, 0); PG8_STAGE(PG8_SA(1, 1), a1 + hstepA, voffA);
;             PG8_WAIT_L(8); PG8_BAR; PG8_WAIT_L(0); PG8_MMA(0, 0, At, B0); PG8_BAR; PG8_SCHED;
;             PG8_LDB(B1, 0, 1); PG8_STAGE(PG8_SB(0, 0), b2, voffB);
;             PG8_BAR; PG8_WAIT_L(0); PG8_MMA(0, 1, At, B1); PG8_BAR;
;             PG8_LDA(At, 0, 1); PG8_STAGE(PG8_SA(0, 0), a2, voffA);
;             PG8_BAR; PG8_WAIT_L(0); PG8_MMA(1, 0, At, B0); PG8_BAR; PG8_SCHED;
.LBB0_439:
	v_readlane_b32 s10, v254, 62
	v_readlane_b32 s11, v254, 63
	s_andn2_b64 vcc, exec, s[10:11]
	s_cbranch_vccnz .LBB0_442
	s_add_u32 s2, s2, 0x80
	s_addc_u32 s3, s3, 0
	s_add_u32 s14, s8, 0x100
	s_addc_u32 s15, s9, 0
	s_mov_b32 s8, 0
	s_waitcnt vmcnt(0)
	s_add_i32 s30, s8, 2
	s_add_u32 s12, s2, 0x80
	s_addc_u32 s9, s3, 0
	s_add_i32 s31, 0, 0x10000
	v_add_u32_e32 v10, s31, v234
	ds_read_b128 v[134:137], v10
	ds_read_b128 v[138:141], v10 offset:1024
	ds_read_b128 v[142:145], v10 offset:2048
	ds_read_b128 v[146:149], v10 offset:3072
	s_cmp_eq_u32 s27, s8
	s_cselect_b32 s8, s74, s12
	s_cselect_b32 s9, s75, s9
	s_cselect_b32 s13, s79, s15
	s_cselect_b32 s12, s78, s14
	v_lshl_add_u64 v[12:13], s[2:3], 0, v[176:177]
	s_add_i32 m0, s65, 0xc000
	ds_read_b128 v[150:153], v240
	ds_read_b128 v[154:157], v240 offset:1024
	ds_read_b128 v[182:185], v240 offset:2048
	ds_read_b128 v[186:189], v240 offset:3072
	ds_read_b128 v[190:193], v240 offset:4096
	ds_read_b128 v[194:197], v240 offset:5120
	ds_read_b128 v[198:201], v240 offset:6144
	ds_read_b128 v[202:205], v240 offset:7168
	global_load_lds_dwordx4 v[12:13], off
	v_lshl_add_u64 v[12:13], s[2:3], 0, v[178:179]
	s_add_i32 m0, s65, 0xe000
	s_nop 0
	global_load_lds_dwordx4 v[12:13], off
	s_waitcnt lgkmcnt(8)
	s_barrier
	s_waitcnt lgkmcnt(0)
	s_setprio 1
	s_waitcnt lgkmcnt(0)
	v_mfma_f32_16x16x32_bf16 v[130:133], v[134:137], v[150:153], 0
	v_mfma_f32_16x16x32_bf16 v[126:129], v[142:145], v[150:153], 0
	v_mfma_f32_16x16x32_bf16 v[114:117], v[134:137], v[182:185], 0
	v_mfma_f32_16x16x32_bf16 v[110:113], v[142:145], v[182:185], 0
	v_mfma_f32_16x16x32_bf16 v[98:101], v[134:137], v[190:193], 0
	v_mfma_f32_16x16x32_bf16 v[94:97], v[142:145], v[190:193], 0
	v_mfma_f32_16x16x32_bf16 v[82:85], v[134:137], v[198:201], 0
	v_mfma_f32_16x16x32_bf16 v[78:81], v[142:145], v[198:201], 0
	v_mfma_f32_16x16x32_bf16 v[130:133], v[138:141], v[154:157], v[130:133]
	v_mfma_f32_16x16x32_bf16 v[126:129], v[146:149], v[154:157], v[126:129]
	v_mfma_f32_16x16x32_bf16 v[114:117], v[138:141], v[186:189], v[114:117]
	v_mfma_f32_16x16x32_bf16 v[110:113], v[146:149], v[186:189], v[110:113]
	v_mfma_f32_16x16x32_bf16 v[98:101], v[138:141], v[194:197], v[98:101]
	v_mfma_f32_16x16x32_bf16 v[94:97], v[146:149], v[194:197], v[94:97]
	v_mfma_f32_16x16x32_bf16 v[82:85], v[138:141], v[202:205], v[82:85]
	v_mfma_f32_16x16x32_bf16 v[78:81], v[146:149], v[202:205], v[78:81]
	s_setprio 0
	s_barrier
	s_add_i32 s36, 0, 0x14000
	s_add_i32 s31, s31, s64
	v_add_u32_e32 v10, s36, v234
	v_lshl_add_u64 v[210:211], s[12:13], 0, v[164:165]
	s_mov_b32 m0, s31
	ds_read_b128 v[206:209], v10
	ds_read_b128 v[242:245], v10 offset:1024
	ds_read_b128 v[246:249], v10 offset:2048
	ds_read_b128 v[250:253], v10 offset:3072
	global_load_lds_dwordx4 v[210:211], off
	v_lshl_add_u64 v[216:217], s[12:13], 0, v[160:161]
	s_add_i32 m0, s31, 0x2000
	s_nop 0
	global_load_lds_dwordx4 v[216:217], off
	s_barrier
	s_waitcnt lgkmcnt(0)
	s_setprio 1
	s_waitcnt lgkmcnt(0)
	v_mfma_f32_16x16x32_bf16 v[122:125], v[206:209], v[150:153], 0
	v_mfma_f32_16x16x32_bf16 v[118:121], v[246:249], v[150:153], 0
	v_mfma_f32_16x16x32_bf16 v[106:109], v[206:209], v[182:185], 0
	v_mfma_f32_16x16x32_bf16 v[102:105], v[246:249], v[182:185], 0
	v_mfma_f32_16x16x32_bf16 v[90:93], v[206:209], v[190:193], 0
	v_mfma_f32_16x16x32_bf16 v[86:89], v[246:249], v[190:193], 0
	v_mfma_f32_16x16x32_bf16 v[74:77], v[206:209], v[198:201], 0
	v_mfma_f32_16x16x32_bf16 v[70:73], v[246:249], v[198:201], 0
	v_mfma_f32_16x16x32_bf16 v[122:125], v[242:245], v[154:157], v[122:125]
	v_mfma_f32_16x16x32_bf16 v[118:121], v[250:253], v[154:157], v[118:121]
	v_mfma_f32_16x16x32_bf16 v[106:109], v[242:245], v[186:189], v[106:109]
	v_mfma_f32_16x16x32_bf16 v[102:105], v[250:253], v[186:189], v[102:105]
	v_mfma_f32_16x16x32_bf16 v[90:93], v[242:245], v[194:197], v[90:93]
	v_mfma_f32_16x16x32_bf16 v[86:89], v[250:253], v[194:197], v[86:89]
	v_mfma_f32_16x16x32_bf16 v[74:77], v[242:245], v[202:205], v[74:77]
	v_mfma_f32_16x16x32_bf16 v[70:73], v[250:253], v[202:205], v[70:73]
	s_setprio 0
	s_mov_b32 m0, s65
	v_lshl_add_u64 v[222:223], s[8:9], 0, v[162:163]
	s_barrier
; #define PG8_STAGE(bufoff, gbase, voff) do { _Pragma("unroll") for (int _i = 0; _i < 2; ++_i) \
;         __builtin_amdgcn_global_load_lds((const unsigned*)((const char*)(gbase) + (voff)[_i]), (LAS unsigned*)(lds + (bufoff) + ldsw + _i * 8192), 16, 0, 0); } while (0)
; #define PG8_LDA(dst, b, h) do { _Pragma("unroll") for (int m = 0; m < 4; ++m) _Pragma("unroll") for (int k = 0; k < 2; ++k) dst[m][k] = *(const LAS bf16x8*)(lds + PG8_SA(b, h) + aoff + m * 2048 + k * 1024); } while (0)
; #define PG8_MMA(ai, bj, At, Bt) do { __builtin_amdgcn_s_setprio(1); _Pragma("unroll") for (int m = 0; m < 4; ++m) _Pragma("unroll") for (int n = 0; n < 2; ++n) _Pragma("unroll") for (int k = 0; k < 2; ++k) \
;         acc[ai][bj][m][n] = __builtin_amdgcn_mfma_f32_16x16x32_bf16(Bt[n][k], At[m][k], acc[ai][bj][m][n], 0, 0, 0); __builtin_amdgcn_s_setprio(0); } while (0)
; #define PG8_WAIT_V(n) asm volatile("s_waitcnt vmcnt(" #n ")" ::: "memory")
; #define PG8_WAIT_L(n) asm volatile("s_waitcnt lgkmcnt(" #n ")" ::: "memory")
; #define PG8_BAR __builtin_amdgcn_s_barrier()
; #define PG8_SCHED __builtin_amdgcn_sched_barrier(0)
; __device__ __forceinline__ void gemm_phase(const int bid, const int nblk, LAS unsigned char* lds, const int garg, const int chunk, const Params& p) {
;     ...
;             PG8_LDA(At, 0, 1); PG8_STAGE(PG8_SA(0, 0), a2, voffA);
;             PG8_BAR; PG8_WAIT_L(0); PG8_MMA(1, 0, At, B0); PG8_BAR; PG8_SCHED;
;             PG8_STAGE(PG8_SB(0, 1), b2 + hstepB, voffB);
;             PG8_WAIT_V(6); PG8_BAR; PG8_MMA(1, 1, At, B1); PG8_BAR;
	ds_read_b128 v[150:153], v240 offset:16384
	ds_read_b128 v[154:157], v240 offset:17408
	ds_read_b128 v[182:185], v240 offset:18432
	ds_read_b128 v[186:189], v240 offset:19456
	ds_read_b128 v[190:193], v240 offset:20480
	ds_read_b128 v[194:197], v240 offset:21504
	ds_read_b128 v[198:201], v240 offset:22528
	ds_read_b128 v[202:205], v240 offset:23552
	global_load_lds_dwordx4 v[222:223], off
	v_lshl_add_u64 v[224:225], s[8:9], 0, v[8:9]
	s_mov_b32 m0, s71
	s_nop 0
	global_load_lds_dwordx4 v[224:225], off
	s_barrier
	s_waitcnt lgkmcnt(0)
	s_setprio 1
	s_waitcnt lgkmcnt(0)
	v_mfma_f32_16x16x32_bf16 v[66:69], v[134:137], v[150:153], 0
	v_mfma_f32_16x16x32_bf16 v[62:65], v[142:145], v[150:153], 0
	v_mfma_f32_16x16x32_bf16 v[50:53], v[134:137], v[182:185], 0
	v_mfma_f32_16x16x32_bf16 v[46:49], v[142:145], v[182:185], 0
	v_mfma_f32_16x16x32_bf16 v[34:37], v[134:137], v[190:193], 0
	v_mfma_f32_16x16x32_bf16 v[30:33], v[142:145], v[190:193], 0
	v_mfma_f32_16x16x32_bf16 v[18:21], v[134:137], v[198:201], 0
	v_mfma_f32_16x16x32_bf16 v[12:15], v[142:145], v[198:201], 0
	v_mfma_f32_16x16x32_bf16 v[66:69], v[138:141], v[154:157], v[66:69]
	v_mfma_f32_16x16x32_bf16 v[62:65], v[146:149], v[154:157], v[62:65]
	v_mfma_f32_16x16x32_bf16 v[50:53], v[138:141], v[186:189], v[50:53]
	v_mfma_f32_16x16x32_bf16 v[46:49], v[146:149], v[186:189], v[46:49]
	v_mfma_f32_16x16x32_bf16 v[34:37], v[138:141], v[194:197], v[34:37]
	v_mfma_f32_16x16x32_bf16 v[30:33], v[146:149], v[194:197], v[30:33]
	v_mfma_f32_16x16x32_bf16 v[18:21], v[138:141], v[202:205], v[18:21]
	v_mfma_f32_16x16x32_bf16 v[12:15], v[146:149], v[202:205], v[12:15]
	s_setprio 0
	s_barrier
	s_add_u32 s12, s12, s66
	s_addc_u32 s13, s13, s67
	s_add_i32 s31, s36, s64
	v_lshl_add_u64 v[220:221], s[12:13], 0, v[164:165]
	s_mov_b32 m0, s31
	v_lshl_add_u64 v[226:227], s[12:13], 0, v[160:161]
	global_load_lds_dwordx4 v[220:221], off
	s_add_i32 m0, s31, 0x2000
	s_nop 0
	global_load_lds_dwordx4 v[226:227], off
	s_waitcnt vmcnt(6)
	s_barrier
	s_setprio 1
	v_mfma_f32_16x16x32_bf16 v[58:61], v[206:209], v[150:153], 0
	v_mfma_f32_16x16x32_bf16 v[54:57], v[246:249], v[150:153], 0
	v_mfma_f32_16x16x32_bf16 v[42:45], v[206:209], v[182:185], 0
	v_mfma_f32_16x16x32_bf16 v[38:41], v[246:249], v[182:185], 0
	v_mfma_f32_16x16x32_bf16 v[26:29], v[206:209], v[190:193], 0
	v_mfma_f32_16x16x32_bf16 v[22:25], v[246:249], v[190:193], 0
	v_mfma_f32_16x16x32_bf16 v[4:7], v[206:209], v[198:201], 0
	v_mfma_f32_16x16x32_bf16 v[0:3], v[246:249], v[198:201], 0
	v_mfma_f32_16x16x32_bf16 v[58:61], v[242:245], v[154:157], v[58:61]
	v_mfma_f32_16x16x32_bf16 v[54:57], v[250:253], v[154:157], v[54:57]
	v_mfma_f32_16x16x32_bf16 v[42:45], v[242:245], v[186:189], v[42:45]
	v_mfma_f32_16x16x32_bf16 v[38:41], v[250:253], v[186:189], v[38:41]
	v_mfma_f32_16x16x32_bf16 v[26:29], v[242:245], v[194:197], v[26:29]
	v_mfma_f32_16x16x32_bf16 v[22:25], v[250:253], v[194:197], v[22:25]
	v_mfma_f32_16x16x32_bf16 v[4:7], v[242:245], v[202:205], v[4:7]
	v_mfma_f32_16x16x32_bf16 v[0:3], v[250:253], v[202:205], v[0:3]
	s_setprio 0
	s_branch .Lk_mid

; #define PG8_STAGE(bufoff, gbase, voff) do { _Pragma("unroll") for (int _i = 0; _i < 2; ++_i) \
;         __builtin_amdgcn_global_load_lds((const unsigned*)((const char*)(gbase) + (voff)[_i]), (LAS unsigned*)(lds + (bufoff) + ldsw + _i * 8192), 16, 0, 0); } while (0)
; #define PG8_LDA(dst, b, h) do { _Pragma("unroll") for (int m = 0; m < 4; ++m) _Pragma("unroll") for (int k = 0; k < 2; ++k) dst[m][k] = *(const LAS bf16x8*)(lds + PG8_SA(b, h) + aoff + m * 2048 + k * 1024); } while (0)
; #define PG8_LDB(dst, b, h) do { _Pragma("unroll") for (int n = 0; n < 2; ++n) _Pragma("unroll") for (int k = 0; k < 2; ++k) dst[n][k] = *(const LAS bf16x8*)(lds + PG8_SB(b, h) + boff + n * 2048 + k * 1024); } while (0)
; #define PG8_MMA(ai, bj, At, Bt) do { __builtin_amdgcn_s_setprio(1); _Pragma("unroll") for (int m = 0; m < 4; ++m) _Pragma("unroll") for (int n = 0; n < 2; ++n) _Pragma("unroll") for (int k = 0; k < 2; ++k) \
;         acc[ai][bj][m][n] = __builtin_amdgcn_mfma_f32_16x16x32_bf16(Bt[n][k], At[m][k], acc[ai][bj][m][n], 0, 0, 0); __builtin_amdgcn_s_setprio(0); } while (0)
; #define PG8_WAIT_L(n) asm volatile("s_waitcnt lgkmcnt(" #n ")" ::: "memory")
; #define PG8_BAR __builtin_amdgcn_s_barrier()
; #define PG8_SCHED __builtin_amdgcn_sched_barrier(0)
; __device__ __forceinline__ void gemm_phase(const int bid, const int nblk, LAS unsigned char* lds, const int garg, const int chunk, const Params& p) {
;     ...
;             PG8_LDB(B0, 1, 0); PG8_SCHED; PG8_LDA(At, 1, 0); PG8_STAGE(PG8_SA(0, 1), a2 + hstepA, voffA);
;             PG8_WAIT_L(8); PG8_BAR; PG8_WAIT_L(0); PG8_MMA(0, 0, At, B0); PG8_BAR; PG8_SCHED;
;             PG8_LDB(B1, 1, 1); PG8_STAGE(PG8_SB(1, 0), b3, voffB);
;             PG8_BAR; PG8_WAIT_L(0); PG8_MMA(0, 1, At, B1); PG8_BAR;
.Lk_mid:
	s_add_i32 s12, 0, 0x18000
	v_add_u32_e32 v10, s12, v234
	s_barrier
	ds_read_b128 v[134:137], v10
	ds_read_b128 v[138:141], v10 offset:1024
	ds_read_b128 v[142:145], v10 offset:2048
	ds_read_b128 v[146:149], v10 offset:3072
	s_add_u32 s8, s8, s88
	s_addc_u32 s9, s9, s89
	s_mov_b32 m0, s63
	v_lshl_add_u64 v[16:17], s[8:9], 0, v[162:163]
	ds_read_b128 v[150:153], v240 offset:32768
	ds_read_b128 v[154:157], v240 offset:33792
	ds_read_b128 v[182:185], v240 offset:34816
	ds_read_b128 v[186:189], v240 offset:35840
	ds_read_b128 v[190:193], v240 offset:36864
	ds_read_b128 v[194:197], v240 offset:37888
	ds_read_b128 v[198:201], v240 offset:38912
	ds_read_b128 v[202:205], v240 offset:39936
	global_load_lds_dwordx4 v[16:17], off
	v_lshl_add_u64 v[16:17], s[8:9], 0, v[8:9]
	s_mov_b32 m0, s19
	s_nop 0
	global_load_lds_dwordx4 v[16:17], off
	s_waitcnt lgkmcnt(8)
	s_barrier
	s_waitcnt lgkmcnt(0)
	s_setprio 1
	s_waitcnt lgkmcnt(0)
	v_mfma_f32_16x16x32_bf16 v[130:133], v[134:137], v[150:153], v[130:133]
	v_mfma_f32_16x16x32_bf16 v[126:129], v[142:145], v[150:153], v[126:129]
	v_mfma_f32_16x16x32_bf16 v[114:117], v[134:137], v[182:185], v[114:117]
	v_mfma_f32_16x16x32_bf16 v[110:113], v[142:145], v[182:185], v[110:113]
	v_mfma_f32_16x16x32_bf16 v[98:101], v[134:137], v[190:193], v[98:101]
	v_mfma_f32_16x16x32_bf16 v[94:97], v[142:145], v[190:193], v[94:97]
	v_mfma_f32_16x16x32_bf16 v[82:85], v[134:137], v[198:201], v[82:85]
	v_mfma_f32_16x16x32_bf16 v[78:81], v[142:145], v[198:201], v[78:81]
	v_mfma_f32_16x16x32_bf16 v[130:133], v[138:141], v[154:157], v[130:133]
	v_mfma_f32_16x16x32_bf16 v[126:129], v[146:149], v[154:157], v[126:129]
	v_mfma_f32_16x16x32_bf16 v[114:117], v[138:141], v[186:189], v[114:117]
	v_mfma_f32_16x16x32_bf16 v[110:113], v[146:149], v[186:189], v[110:113]
	v_mfma_f32_16x16x32_bf16 v[98:101], v[138:141], v[194:197], v[98:101]
	v_mfma_f32_16x16x32_bf16 v[94:97], v[146:149], v[194:197], v[94:97]
	v_mfma_f32_16x16x32_bf16 v[82:85], v[138:141], v[202:205], v[82:85]
	v_mfma_f32_16x16x32_bf16 v[78:81], v[146:149], v[202:205], v[78:81]
	s_setprio 0
	s_barrier
	s_add_i32 s8, 0, 0x1c000
	s_add_i32 s9, s12, s64
	v_add_u32_e32 v10, s8, v234
	v_lshl_add_u64 v[16:17], v[210:211], 0, s[92:93]
	s_mov_b32 m0, s9
	ds_read_b128 v[206:209], v10
	ds_read_b128 v[242:245], v10 offset:1024
	ds_read_b128 v[246:249], v10 offset:2048
	ds_read_b128 v[250:253], v10 offset:3072
	global_load_lds_dwordx4 v[16:17], off
	v_lshl_add_u64 v[16:17], v[216:217], 0, s[92:93]
	s_add_i32 m0, s9, 0x2000
	s_nop 0
	global_load_lds_dwordx4 v[16:17], off
	s_barrier
	s_waitcnt lgkmcnt(0)
	s_setprio 1
	s_waitcnt lgkmcnt(0)
	v_mfma_f32_16x16x32_bf16 v[122:125], v[206:209], v[150:153], v[122:125]
	v_mfma_f32_16x16x32_bf16 v[118:121], v[246:249], v[150:153], v[118:121]
	v_mfma_f32_16x16x32_bf16 v[106:109], v[206:209], v[182:185], v[106:109]
	v_mfma_f32_16x16x32_bf16 v[102:105], v[246:249], v[182:185], v[102:105]
	v_mfma_f32_16x16x32_bf16 v[90:93], v[206:209], v[190:193], v[90:93]
	v_mfma_f32_16x16x32_bf16 v[86:89], v[246:249], v[190:193], v[86:89]
	v_mfma_f32_16x16x32_bf16 v[74:77], v[206:209], v[198:201], v[74:77]
	v_mfma_f32_16x16x32_bf16 v[70:73], v[246:249], v[198:201], v[70:73]
	v_mfma_f32_16x16x32_bf16 v[122:125], v[242:245], v[154:157], v[122:125]
	v_mfma_f32_16x16x32_bf16 v[118:121], v[250:253], v[154:157], v[118:121]
	v_mfma_f32_16x16x32_bf16 v[106:109], v[242:245], v[186:189], v[106:109]
	v_mfma_f32_16x16x32_bf16 v[102:105], v[250:253], v[186:189], v[102:105]
	v_mfma_f32_16x16x32_bf16 v[90:93], v[242:245], v[194:197], v[90:93]
	v_mfma_f32_16x16x32_bf16 v[86:89], v[250:253], v[194:197], v[86:89]
	v_mfma_f32_16x16x32_bf16 v[74:77], v[242:245], v[202:205], v[74:77]
	v_mfma_f32_16x16x32_bf16 v[70:73], v[250:253], v[202:205], v[70:73]
	s_setprio 0
	s_mov_b32 m0, s70
	v_lshl_add_u64 v[16:17], v[222:223], 0, s[92:93]
	s_barrier
; #define PG8_STAGE(bufoff, gbase, voff) do { _Pragma("unroll") for (int _i = 0; _i < 2; ++_i) \
;         __builtin_amdgcn_global_load_lds((const unsigned*)((const char*)(gbase) + (voff)[_i]), (LAS unsigned*)(lds + (bufoff) + ldsw + _i * 8192), 16, 0, 0); } while (0)
; #define PG8_LDA(dst, b, h) do { _Pragma("unroll") for (int m = 0; m < 4; ++m) _Pragma("unroll") for (int k = 0; k < 2; ++k) dst[m][k] = *(const LAS bf16x8*)(lds + PG8_SA(b, h) + aoff + m * 2048 + k * 1024); } while (0)
; #define PG8_MMA(ai, bj, At, Bt) do { __builtin_amdgcn_s_setprio(1); _Pragma("unroll") for (int m = 0; m < 4; ++m) _Pragma("unroll") for (int n = 0; n < 2; ++n) _Pragma("unroll") for (int k = 0; k < 2; ++k) \
;         acc[ai][bj][m][n] = __builtin_amdgcn_mfma_f32_16x16x32_bf16(Bt[n][k], At[m][k], acc[ai][bj][m][n], 0, 0, 0); __builtin_amdgcn_s_setprio(0); } while (0)
; #define PG8_WAIT_V(n) asm volatile("s_waitcnt vmcnt(" #n ")" ::: "memory")
; #define PG8_WAIT_L(n) asm volatile("s_waitcnt lgkmcnt(" #n ")" ::: "memory")
; #define PG8_BAR __builtin_amdgcn_s_barrier()
; #define PG8_SCHED __builtin_amdgcn_sched_barrier(0)
; __device__ __forceinline__ void gemm_phase(const int bid, const int nblk, LAS unsigned char* lds, const int garg, const int chunk, const Params& p) {
;     ...
;             PG8_LDA(At, 1, 1); PG8_STAGE(PG8_SA(1, 0), a3, voffA);
;             PG8_BAR; PG8_WAIT_L(0); PG8_MMA(1, 0, At, B0); PG8_BAR; PG8_SCHED;
;             PG8_STAGE(PG8_SB(1, 1), b3 + hstepB, voffB);
;             PG8_WAIT_V(6); PG8_BAR; PG8_MMA(1, 1, At, B1); PG8_BAR;
;         }
	ds_read_b128 v[150:153], v240 offset:49152
	ds_read_b128 v[154:157], v240 offset:50176
	ds_read_b128 v[182:185], v240 offset:51200
	ds_read_b128 v[186:189], v240 offset:52224
	ds_read_b128 v[190:193], v240 offset:53248
	ds_read_b128 v[194:197], v240 offset:54272
	ds_read_b128 v[198:201], v240 offset:55296
	ds_read_b128 v[202:205], v240 offset:56320
	global_load_lds_dwordx4 v[16:17], off
	v_lshl_add_u64 v[16:17], v[224:225], 0, s[92:93]
	s_mov_b32 m0, s54
	s_nop 0
	global_load_lds_dwordx4 v[16:17], off
	s_barrier
	s_waitcnt lgkmcnt(0)
	s_setprio 1
	s_waitcnt lgkmcnt(0)
	v_mfma_f32_16x16x32_bf16 v[66:69], v[134:137], v[150:153], v[66:69]
	v_mfma_f32_16x16x32_bf16 v[62:65], v[142:145], v[150:153], v[62:65]
	v_mfma_f32_16x16x32_bf16 v[50:53], v[134:137], v[182:185], v[50:53]
	v_mfma_f32_16x16x32_bf16 v[46:49], v[142:145], v[182:185], v[46:49]
	v_mfma_f32_16x16x32_bf16 v[34:37], v[134:137], v[190:193], v[34:37]
	v_mfma_f32_16x16x32_bf16 v[30:33], v[142:145], v[190:193], v[30:33]
	v_mfma_f32_16x16x32_bf16 v[16:19], v[134:137], v[198:201], v[18:21]
	v_mfma_f32_16x16x32_bf16 v[12:15], v[142:145], v[198:201], v[12:15]
	v_mfma_f32_16x16x32_bf16 v[66:69], v[138:141], v[154:157], v[66:69]
	v_mfma_f32_16x16x32_bf16 v[62:65], v[146:149], v[154:157], v[62:65]
	v_mfma_f32_16x16x32_bf16 v[50:53], v[138:141], v[186:189], v[50:53]
	v_mfma_f32_16x16x32_bf16 v[46:49], v[146:149], v[186:189], v[46:49]
	v_mfma_f32_16x16x32_bf16 v[34:37], v[138:141], v[194:197], v[34:37]
	v_mfma_f32_16x16x32_bf16 v[30:33], v[146:149], v[194:197], v[30:33]
	v_mfma_f32_16x16x32_bf16 v[18:21], v[138:141], v[202:205], v[16:19]
	v_mfma_f32_16x16x32_bf16 v[14:17], v[146:149], v[202:205], v[12:15]
	s_setprio 0
	s_barrier
	s_add_i32 s8, s8, s64
	v_lshl_add_u64 v[12:13], v[220:221], 0, s[92:93]
	s_mov_b32 m0, s8
	s_nop 0
	global_load_lds_dwordx4 v[12:13], off
	v_lshl_add_u64 v[12:13], v[226:227], 0, s[92:93]
	s_add_i32 m0, s8, 0x2000
	s_nop 0
	global_load_lds_dwordx4 v[12:13], off
	s_waitcnt vmcnt(6)
	s_barrier
	s_setprio 1
	v_mfma_f32_16x16x32_bf16 v[58:61], v[206:209], v[150:153], v[58:61]
	v_mfma_f32_16x16x32_bf16 v[54:57], v[246:249], v[150:153], v[54:57]
	v_mfma_f32_16x16x32_bf16 v[42:45], v[206:209], v[182:185], v[42:45]
	v_mfma_f32_16x16x32_bf16 v[38:41], v[246:249], v[182:185], v[38:41]
	v_mfma_f32_16x16x32_bf16 v[26:29], v[206:209], v[190:193], v[26:29]
	v_mfma_f32_16x16x32_bf16 v[22:25], v[246:249], v[190:193], v[22:25]
	v_mfma_f32_16x16x32_bf16 v[4:7], v[206:209], v[198:201], v[4:7]
	v_mfma_f32_16x16x32_bf16 v[0:3], v[246:249], v[198:201], v[0:3]
	v_mfma_f32_16x16x32_bf16 v[58:61], v[242:245], v[154:157], v[58:61]
	v_mfma_f32_16x16x32_bf16 v[54:57], v[250:253], v[154:157], v[54:57]
	v_mfma_f32_16x16x32_bf16 v[42:45], v[242:245], v[186:189], v[42:45]
	v_mfma_f32_16x16x32_bf16 v[38:41], v[250:253], v[186:189], v[38:41]
	v_mfma_f32_16x16x32_bf16 v[26:29], v[242:245], v[194:197], v[26:29]
	v_mfma_f32_16x16x32_bf16 v[22:25], v[250:253], v[194:197], v[22:25]
	v_mfma_f32_16x16x32_bf16 v[4:7], v[242:245], v[202:205], v[4:7]
	v_mfma_f32_16x16x32_bf16 v[0:3], v[250:253], v[202:205], v[0:3]
	s_setprio 0
	s_add_u32 s2, s2, 0x100
	s_addc_u32 s3, s3, 0
	s_add_u32 s14, s14, 0x100
	s_addc_u32 s15, s15, 0
	s_cmp_ge_i32 s30, s55
	s_mov_b32 s8, s30
	s_barrier
	s_cbranch_scc0 .LBB0_441
	s_branch .LBB0_443
